# attention chunk-2 norm reductions run as four parallel chains; pool-GEMM column-scale loads issued together
# speedup vs baseline: 1.0021x; 1.0001x over previous
.LBB0_202:
	ds_bpermute_b32 v0, v217, v134
	v_mov_b32_e32 v7, v210
	v_readlane_b32 s12, v254, 49
	v_readlane_b32 s13, v254, 50
	s_waitcnt lgkmcnt(0)
	v_add_f32_e32 v0, v134, v0
	ds_bpermute_b32 v2, v218, v0
	v_ashrrev_i32_e32 v129, 31, v128
	v_lshl_add_u64 v[4:5], s[12:13], 0, v[128:129]
	v_readlane_b32 s2, v254, 43
	v_readlane_b32 s3, v254, 44
	s_waitcnt lgkmcnt(0)
	v_add_f32_e32 v0, v0, v2
	ds_bpermute_b32 v2, v217, v135
	v_readlane_b32 s0, v254, 63
	s_lshl_b32 s0, s0, 1
	v_ashrrev_i32_e32 v7, 2, v7
	v_and_b32_e32 v8, -4, v7
	s_waitcnt lgkmcnt(0)
	v_add_f32_e32 v2, v135, v2
	ds_bpermute_b32 v3, v218, v2
	v_ashrrev_i32_e32 v9, 31, v8
	s_mov_b32 s15, s1
	s_sub_i32 s93, 0x7f, s7
	s_lshl_b32 s92, s93, 6
	s_waitcnt lgkmcnt(0)
	v_add_f32_e32 v6, v2, v3
	v_lshlrev_b64 v[2:3], 11, v[4:5]
	v_lshl_add_u64 v[2:3], s[2:3], 0, v[2:3]
	v_readlane_b32 s2, v254, 60
	v_lshl_add_u64 v[2:3], v[2:3], 0, s[0:1]
	v_readlane_b32 s3, v254, 61
	v_readlane_b32 s0, v254, 57
	s_or_b32 s0, s92, s0
	v_lshl_add_u64 v[2:3], s[2:3], 1, v[2:3]
	v_lshl_add_u64 v[2:3], v[8:9], 1, v[2:3]
	v_mov_b64_e32 v[8:9], s[10:11]
	v_mad_u64_u32 v[8:9], s[2:3], v4, s23, v[8:9]
	v_mad_i32_i24 v9, v5, s23, v9
	v_readlane_b32 s2, v254, 47
	v_lshl_add_u64 v[4:5], v[8:9], 0, s[14:15]
	v_readlane_b32 s3, v254, 48
	v_or_b32_e32 v172, s0, v211
	v_ashrrev_i32_e32 v173, 31, v172
	v_lshl_add_u64 v[4:5], s[2:3], 1, v[4:5]
	global_load_ushort v7, v[4:5], off offset:2564
	s_movk_i32 s0, 0x7cf
	s_waitcnt vmcnt(0)
	v_lshlrev_b32_e32 v7, 16, v7
	v_mul_f32_e32 v7, 0xbfb8aa3b, v7
	v_exp_f32_e32 v7, v7
	s_nop 0
	v_add_f32_e32 v7, 1.0, v7
	v_div_scale_f32 v8, s[2:3], v7, v7, 1.0
	v_rcp_f32_e32 v9, v8
	s_nop 0
	v_fma_f32 v10, -v8, v9, 1.0
	v_fmac_f32_e32 v9, v10, v9
	v_div_scale_f32 v10, vcc, 1.0, v7, 1.0
	v_mul_f32_e32 v11, v10, v9
	v_fma_f32 v12, -v8, v11, v10
	v_fmac_f32_e32 v11, v12, v9
	v_fma_f32 v8, -v8, v11, v10
	v_div_fmas_f32 v8, v8, v9, v11
	v_div_fixup_f32 v7, v8, v7, 1.0
	v_div_scale_f32 v8, s[2:3], v0, v0, v7
	v_rcp_f32_e32 v9, v8
	s_nop 0
	v_fma_f32 v10, -v8, v9, 1.0
	v_fmac_f32_e32 v9, v10, v9
	v_div_scale_f32 v10, vcc, v7, v0, v7
	v_mul_f32_e32 v11, v10, v9
	v_fma_f32 v12, -v8, v11, v10
	v_fmac_f32_e32 v11, v12, v9
	v_fma_f32 v8, -v8, v11, v10
	v_div_fmas_f32 v8, v8, v9, v11
	v_div_fixup_f32 v0, v8, v0, v7
	ds_read_b128 v[8:11], v224
	s_waitcnt lgkmcnt(0)
	v_pk_fma_f32 v[10:11], v[86:87], v[0:1], v[10:11] op_sel_hi:[1,0,1]
	v_pk_fma_f32 v[8:9], v[84:85], v[0:1], v[8:9] op_sel_hi:[1,0,1]
	s_nop 0
	v_cvt_pk_bf16_f32 v8, v8, v9
	v_cvt_pk_bf16_f32 v9, v10, v11
	global_store_dwordx2 v[2:3], v[8:9], off
	ds_read_b128 v[8:11], v224 offset:1024
	s_waitcnt lgkmcnt(0)
	v_pk_fma_f32 v[10:11], v[90:91], v[0:1], v[10:11] op_sel_hi:[1,0,1]
	v_pk_fma_f32 v[8:9], v[88:89], v[0:1], v[8:9] op_sel_hi:[1,0,1]
	s_nop 0
	v_cvt_pk_bf16_f32 v8, v8, v9
	v_cvt_pk_bf16_f32 v9, v10, v11
	global_store_dwordx2 v[2:3], v[8:9], off offset:32
	ds_read_b128 v[8:11], v224 offset:2048
	s_waitcnt lgkmcnt(0)
	v_pk_fma_f32 v[10:11], v[94:95], v[0:1], v[10:11] op_sel_hi:[1,0,1]
	v_pk_fma_f32 v[8:9], v[92:93], v[0:1], v[8:9] op_sel_hi:[1,0,1]
	s_nop 0
	v_cvt_pk_bf16_f32 v8, v8, v9
	v_cvt_pk_bf16_f32 v9, v10, v11
	global_store_dwordx2 v[2:3], v[8:9], off offset:64
	ds_read_b128 v[8:11], v224 offset:3072
	s_waitcnt lgkmcnt(0)
	v_pk_fma_f32 v[10:11], v[82:83], v[0:1], v[10:11] op_sel_hi:[1,0,1]
	v_pk_fma_f32 v[8:9], v[80:81], v[0:1], v[8:9] op_sel_hi:[1,0,1]
	s_nop 0
	v_cvt_pk_bf16_f32 v8, v8, v9
	v_cvt_pk_bf16_f32 v9, v10, v11
	global_store_dwordx2 v[2:3], v[8:9], off offset:96
	global_load_ushort v0, v[4:5], off offset:2570
	s_waitcnt vmcnt(0)
	v_lshlrev_b32_e32 v0, 16, v0
	v_mul_f32_e32 v0, 0xbfb8aa3b, v0
	v_exp_f32_e32 v0, v0
	s_nop 0
	v_add_f32_e32 v0, 1.0, v0
	v_div_scale_f32 v4, s[2:3], v0, v0, 1.0
	v_rcp_f32_e32 v5, v4
	s_nop 0
	v_fma_f32 v7, -v4, v5, 1.0
	v_fmac_f32_e32 v5, v7, v5
	v_div_scale_f32 v7, vcc, 1.0, v0, 1.0
	v_mul_f32_e32 v8, v7, v5
	v_fma_f32 v9, -v4, v8, v7
	v_fmac_f32_e32 v8, v9, v5
	v_fma_f32 v4, -v4, v8, v7
	v_div_fmas_f32 v4, v4, v5, v8
	v_div_fixup_f32 v0, v4, v0, 1.0
	v_div_scale_f32 v4, s[2:3], v6, v6, v0
	v_rcp_f32_e32 v5, v4
	v_readlane_b32 s2, v255, 0
	v_readlane_b32 s3, v255, 1
	v_fma_f32 v7, -v4, v5, 1.0
	v_fmac_f32_e32 v5, v7, v5
	v_div_scale_f32 v7, vcc, v0, v6, v0
	v_mul_f32_e32 v8, v7, v5
	v_fma_f32 v9, -v4, v8, v7
	v_fmac_f32_e32 v8, v9, v5
	v_fma_f32 v4, -v4, v8, v7
	v_div_fmas_f32 v4, v4, v5, v8
	v_div_fixup_f32 v0, v4, v6, v0
	ds_read_b128 v[4:7], v224 offset:4096
	s_waitcnt lgkmcnt(0)
	v_pk_fma_f32 v[6:7], v[62:63], v[0:1], v[6:7] op_sel_hi:[1,0,1]
	v_pk_fma_f32 v[4:5], v[60:61], v[0:1], v[4:5] op_sel_hi:[1,0,1]
	s_nop 0
	v_cvt_pk_bf16_f32 v4, v4, v5
	v_cvt_pk_bf16_f32 v5, v6, v7
	global_store_dwordx2 v[2:3], v[4:5], off offset:128
	ds_read_b128 v[4:7], v224 offset:5120
	s_waitcnt lgkmcnt(0)
	v_pk_fma_f32 v[6:7], v[66:67], v[0:1], v[6:7] op_sel_hi:[1,0,1]
	v_pk_fma_f32 v[4:5], v[64:65], v[0:1], v[4:5] op_sel_hi:[1,0,1]
	s_nop 0
	v_cvt_pk_bf16_f32 v4, v4, v5
	v_cvt_pk_bf16_f32 v5, v6, v7
	global_store_dwordx2 v[2:3], v[4:5], off offset:160
	ds_read_b128 v[4:7], v224 offset:6144
	s_waitcnt lgkmcnt(0)
	v_pk_fma_f32 v[6:7], v[38:39], v[0:1], v[6:7] op_sel_hi:[1,0,1]
	v_pk_fma_f32 v[4:5], v[36:37], v[0:1], v[4:5] op_sel_hi:[1,0,1]
	s_nop 0
	v_cvt_pk_bf16_f32 v4, v4, v5
	v_cvt_pk_bf16_f32 v5, v6, v7
	global_store_dwordx2 v[2:3], v[4:5], off offset:192
	ds_read_b128 v[4:7], v224 offset:7168
	s_waitcnt lgkmcnt(0)
	v_pk_fma_f32 v[6:7], v[34:35], v[0:1], v[6:7] op_sel_hi:[1,0,1]
	v_pk_fma_f32 v[4:5], v[32:33], v[0:1], v[4:5] op_sel_hi:[1,0,1]
	s_nop 0
	v_cvt_pk_bf16_f32 v4, v4, v5
	v_cvt_pk_bf16_f32 v5, v6, v7
	global_store_dwordx2 v[2:3], v[4:5], off offset:224
	v_lshl_add_u64 v[2:3], s[12:13], 0, v[172:173]
	v_lshlrev_b64 v[2:3], 10, v[2:3]
	v_lshl_add_u64 v[2:3], v[164:165], 0, v[2:3]
	v_lshl_add_u64 v[2:3], s[2:3], 1, v[2:3]
	s_barrier
	global_load_dwordx4 v[4:7], v[2:3], off
	global_load_dwordx4 v[8:11], v[2:3], off offset:64
	global_load_dwordx4 v[12:15], v[2:3], off offset:128
	global_load_dwordx4 v[16:19], v[2:3], off offset:192
	global_load_dword v0, v[166:167], off
	global_load_dword v43, v[168:169], off
	global_load_dword v44, v[168:169], off offset:256
	global_load_dword v45, v[168:169], off offset:512
	s_mov_b64 s[2:3], 0
	s_waitcnt vmcnt(0)
	v_and_b32_e32 v21, 0x7fffffff, v0
	v_and_b32_e32 v23, 0x7fffffff, v43
	v_and_b32_e32 v25, 0x7fffffff, v44
	v_and_b32_e32 v225, 0x7fffffff, v45
	ds_bpermute_b32 v21, v213, v21
	ds_bpermute_b32 v23, v213, v23
	ds_bpermute_b32 v25, v213, v25
	ds_bpermute_b32 v225, v213, v225
	v_max_f32_e64 v20, |v0|, |v0|
	v_max_f32_e64 v22, |v43|, |v43|
	v_max_f32_e64 v24, |v44|, |v44|
	v_max_f32_e64 v173, |v45|, |v45|
	s_waitcnt lgkmcnt(0)
	v_max_f32_e32 v21, v21, v21
	v_max_f32_e32 v20, v20, v21
	v_max_f32_e32 v23, v23, v23
	v_max_f32_e32 v22, v22, v23
	v_max_f32_e32 v25, v25, v25
	v_max_f32_e32 v24, v24, v25
	v_max_f32_e32 v225, v225, v225
	v_max_f32_e32 v173, v173, v225
	ds_bpermute_b32 v21, v214, v20
	ds_bpermute_b32 v23, v214, v22
	ds_bpermute_b32 v25, v214, v24
	ds_bpermute_b32 v225, v214, v173
	s_waitcnt lgkmcnt(0)
	v_max_f32_e32 v21, v21, v21
	v_max_f32_e32 v20, v20, v21
	v_max_f32_e32 v23, v23, v23
	v_max_f32_e32 v22, v22, v23
	v_max_f32_e32 v25, v25, v25
	v_max_f32_e32 v24, v24, v25
	v_max_f32_e32 v225, v225, v225
	v_max_f32_e32 v173, v173, v225
	ds_bpermute_b32 v21, v215, v20
	ds_bpermute_b32 v23, v215, v22
	ds_bpermute_b32 v25, v215, v24
	ds_bpermute_b32 v225, v215, v173
	s_waitcnt lgkmcnt(0)
	v_max_f32_e32 v21, v21, v21
	v_max_f32_e32 v20, v20, v21
	v_max_f32_e32 v23, v23, v23
	v_max_f32_e32 v22, v22, v23
	v_max_f32_e32 v25, v25, v25
	v_max_f32_e32 v24, v24, v25
	v_max_f32_e32 v225, v225, v225
	v_max_f32_e32 v173, v173, v225
	ds_bpermute_b32 v21, v216, v20
	ds_bpermute_b32 v23, v216, v22
	ds_bpermute_b32 v25, v216, v24
	ds_bpermute_b32 v225, v216, v173
	s_waitcnt lgkmcnt(0)
	v_max_f32_e32 v21, v21, v21
	v_max_f32_e32 v20, v20, v21
	v_max_f32_e32 v23, v23, v23
	v_max_f32_e32 v22, v22, v23
	v_max_f32_e32 v25, v25, v25
	v_max_f32_e32 v24, v24, v25
	v_max_f32_e32 v225, v225, v225
	v_max_f32_e32 v173, v173, v225
	ds_bpermute_b32 v21, v217, v20
	ds_bpermute_b32 v23, v217, v22
	ds_bpermute_b32 v25, v217, v24
	ds_bpermute_b32 v225, v217, v173
	s_waitcnt lgkmcnt(0)
	v_max_f32_e32 v21, v21, v21
	v_max_f32_e32 v20, v20, v21
	v_max_f32_e32 v23, v23, v23
	v_max_f32_e32 v22, v22, v23
	v_max_f32_e32 v25, v25, v25
	v_max_f32_e32 v24, v24, v25
	v_max_f32_e32 v225, v225, v225
	v_max_f32_e32 v173, v173, v225
	ds_bpermute_b32 v21, v218, v20
	ds_bpermute_b32 v23, v218, v22
	ds_bpermute_b32 v25, v218, v24
	ds_bpermute_b32 v225, v218, v173
	v_mov_b32_e32 v0, v221
	v_mov_b32_e32 v2, v220

.LBB0_685:
	v_lshl_or_b32 v164, s0, 8, v176
	v_readlane_b32 s12, v254, 40
	v_ashrrev_i32_e32 v165, 31, v164
	v_readlane_b32 s13, v254, 41
	v_cndmask_b32_e64 v38, 0, 1, s[48:49]
	v_mov_b64_e32 v[52:53], s[46:47]
	v_lshl_add_u64 v[166:167], v[164:165], 2, s[12:13]
	v_cmp_ne_u32_e64 s[38:39], 1, v38
	s_andn2_b64 vcc, exec, s[48:49]
	v_mov_b64_e32 v[50:51], s[44:45]
	s_cbranch_vccnz .LBB0_687
	global_load_dwordx4 v[38:41], v[166:167], off
	global_load_dwordx4 v[212:215], v[166:167], off offset:16
	global_load_dwordx4 v[216:219], v[166:167], off offset:512
	global_load_dwordx4 v[220:223], v[166:167], off offset:528
	s_waitcnt vmcnt(0)
	v_pk_mul_f32 v[52:53], s[46:47], v[40:41]
	v_pk_mul_f32 v[50:51], s[44:45], v[38:39]
.LBB0_687:
	v_mov_b64_e32 v[56:57], s[46:47]
	s_and_b64 vcc, exec, s[38:39]
	v_mov_b64_e32 v[54:55], s[44:45]
	s_cbranch_vccnz .LBB0_689
	v_mov_b32_e32 v38, v212
	v_mov_b32_e32 v39, v213
	v_mov_b32_e32 v40, v214
	v_mov_b32_e32 v41, v215
	s_waitcnt vmcnt(0)
	v_pk_mul_f32 v[56:57], s[46:47], v[40:41]
	v_pk_mul_f32 v[54:55], s[44:45], v[38:39]
.LBB0_689:
	v_mov_b64_e32 v[38:39], s[44:45]
	s_and_b64 vcc, exec, s[38:39]
	v_mov_b64_e32 v[40:41], s[46:47]
	s_cbranch_vccnz .LBB0_691
	v_mov_b32_e32 v38, v216
	v_mov_b32_e32 v39, v217
	v_mov_b32_e32 v40, v218
	v_mov_b32_e32 v41, v219
	s_waitcnt vmcnt(0)
	v_pk_mul_f32 v[40:41], s[46:47], v[40:41]
	v_pk_mul_f32 v[38:39], s[44:45], v[38:39]
.LBB0_691:
	v_mov_b64_e32 v[48:49], s[46:47]
	s_and_b64 vcc, exec, s[38:39]
	v_mov_b64_e32 v[46:47], s[44:45]
	s_cbranch_vccnz .LBB0_693
	v_mov_b32_e32 v46, v220
	v_mov_b32_e32 v47, v221
	v_mov_b32_e32 v48, v222
	v_mov_b32_e32 v49, v223
	s_waitcnt vmcnt(0)
	v_pk_mul_f32 v[48:49], s[46:47], v[48:49]
	v_pk_mul_f32 v[46:47], s[44:45], v[46:47]
